# workgroups that skip the preparation run the decode stream on both wave groups for their first two pulls, then group 0 goes to the prompt attention units
# speedup vs baseline: 1.0044x; 1.0044x over previous
; #define LAS __attribute__((address_space(3)))
; __device__ __forceinline__ void sb_decode_wave_loop(const Params& P, float* lds) {
;     unsigned* qd = (unsigned*)(P.ws + WS_BAR) + QW_DEC;
;     const int lane = threadIdx.x & 63;
;     volatile LAS unsigned* scw = (volatile LAS unsigned*)((LAS unsigned char*)lds + SC_CTL_OFF_FWD);
;     unsigned nxt = 0u;
;     if (lane == 0) nxt = atomicAdd(qd, 2u);
;     for (;;) {
;         const int t = __builtin_amdgcn_readfirstlane((int)nxt);
;         if (t >= DEC_NTASK) break;
;         if (lane == 0) nxt = atomicAdd(qd, 2u);
;         bool thin = false;
;         bool scan_running = false;
;         if (SC_THIN && blockIdx.x < 96) { constexpr unsigned NCHU = SEQ / 16; scan_running = scw[1] < NCHU || scw[2] < NCHU || scw[3] < NCHU || scw[4] < NCHU; thin = scan_running; }
;         thin = true;
;         if (blockIdx.x < 96 && scan_running) { sb_decode_task<4>(P, lds, t); sb_decode_task<4>(P, lds, t + 1); }
;         else if (thin) { sb_decode_task<8>(P, lds, t); sb_decode_task<8>(P, lds, t + 1); }
;         else { sb_decode_task<16>(P, lds, t); sb_decode_task<16>(P, lds, t + 1); }
;     }
; __device__ __forceinline__ void p3_scan_and_sb(const Params& P, float* lds) {
;     ...
;     } else {
;         const int grp = wave >> 2, gw = wave & 3;
;         volatile LAS unsigned* gctl = (volatile LAS unsigned*)((LAS unsigned char*)lds + LDS_CTL + 32);
;         if (tid < 8) gctl[tid] = 0u;
;         __syncthreads();
;         sba::Grp4 G; G.ctr = gctl + grp; G.gen = 0u;
;         if (grp == 1) sb_decode_wave_loop(P, lds);
.LBB0_939:
	s_cmp_lt_i32 s60, 4
	s_cselect_b64 s[0:1], -1, 0
	s_cmp_gt_i32 s61, 3
	s_cselect_b64 s[2:3], -1, 0
	s_and_b64 s[34:35], s[0:1], s[2:3]
	s_andn2_b64 vcc, exec, s[34:35]
	s_cbranch_vccnz .LBB0_1576
	v_writelane_b32 v252, s34, 54
	s_cmpk_lt_u32 s56, 0x60
	v_and_b32_e32 v1, 63, v0
	v_writelane_b32 v252, s35, 55
	v_writelane_b32 v252, s80, 56
	s_cselect_b64 s[52:53], -1, 0
	s_cmpk_gt_u32 s56, 0x5f
	v_writelane_b32 v252, s81, 57
	v_writelane_b32 v252, s56, 53
	v_writelane_b32 v252, s60, 51
	s_mov_b64 s[0:1], -1
	s_waitcnt vmcnt(0)
	v_writelane_b32 v252, s61, 52
	s_barrier
	v_writelane_b32 v252, s57, 50
	s_cbranch_scc0 .LBB0_1203
	v_writelane_b32 v252, s52, 58
	v_cmp_gt_u32_e32 vcc, 8, v0
	s_nop 0
	v_writelane_b32 v252, s53, 59
	s_and_saveexec_b64 s[0:1], vcc
	v_lshl_add_u32 v2, v0, 2, 0
	v_add_u32_e32 v2, 0x26020, v2
	v_mov_b32_e32 v3, 0
	ds_write_b32 v2, v3
	s_or_b64 exec, exec, s[0:1]
	v_lshrrev_b32_e32 v94, 8, v0
	s_waitcnt lgkmcnt(0)
	s_barrier
	v_cmp_eq_u32_e32 vcc, 1, v94
	s_mov_b64 s[0:1], exec
	v_writelane_b32 v252, s0, 60
	s_nop 1
	v_writelane_b32 v252, s1, 61
	s_cmpk_gt_u32 s56, 0xaa
	s_cselect_b64 s[2:3], exec, 0
	s_or_b64 vcc, vcc, s[2:3]
	s_and_b64 s[0:1], s[0:1], vcc
	s_mov_b64 exec, s[0:1]
	s_cbranch_execz .LBB0_1092
	v_readfirstlane_b32 s2, v94
	s_cmp_eq_u32 s2, 0
	s_cselect_b32 s100, 1, 0x7fffffff
	s_add_u32 s0, s78, 0x3900
	s_addc_u32 s1, s79, 0
	v_writelane_b32 v252, s0, 62
	v_mov_b32_e32 v95, 0
	v_cmp_eq_u32_e64 s[4:5], 0, v1
	v_writelane_b32 v252, s1, 63
	s_and_saveexec_b64 s[0:1], s[4:5]
	v_readlane_b32 s22, v252, 48
	v_readlane_b32 s23, v252, 49
	s_cbranch_execz .LBB0_948
	s_mov_b64 s[6:7], exec
	v_mbcnt_lo_u32_b32 v2, s6, 0
	v_mbcnt_hi_u32_b32 v2, s7, v2
	v_cmp_eq_u32_e32 vcc, 0, v2
	s_and_saveexec_b64 s[2:3], vcc
	s_cbranch_execz .LBB0_947
	s_bcnt1_i32_b64 s6, s[6:7]
	s_lshl_b32 s6, s6, 1
	v_mov_b32_e32 v4, s6
	v_readlane_b32 s6, v252, 62
	v_mov_b32_e32 v3, 0
	v_readlane_b32 s7, v252, 63
	s_nop 4
	global_atomic_add v3, v3, v4, s[6:7] sc0

; __device__ __forceinline__ void sb_decode_wave_loop(const Params& P, float* lds) {
;     ...
;     for (;;) {
;         const int t = __builtin_amdgcn_readfirstlane((int)nxt);
;         if (t >= DEC_NTASK) break;
;         if (lane == 0) nxt = atomicAdd(qd, 2u);
.Ledc_last:
	v_mov_b32_e32 v95, 0x6000
	s_mov_b64 s[0:1], exec
	s_branch .LBB0_956

; __device__ __forceinline__ void sb_decode_wave_loop(const Params& P, float* lds) {
;     ...
;     for (;;) {
;         const int t = __builtin_amdgcn_readfirstlane((int)nxt);
;         if (t >= DEC_NTASK) break;
;         if (lane == 0) nxt = atomicAdd(qd, 2u);
.LBB0_951:
	v_readfirstlane_b32 s34, v95
	s_cmpk_gt_i32 s34, 0x5fff
	s_mov_b64 s[0:1], -1
	s_cbranch_scc1 .LBB0_950
	s_cmp_eq_u32 s100, 0
	s_cbranch_scc1 .Ledc_last
	s_sub_i32 s100, s100, 1
	s_and_saveexec_b64 s[0:1], s[4:5]
	s_cbranch_execz .LBB0_956
	s_mov_b64 s[36:37], exec
	v_mbcnt_lo_u32_b32 v2, s36, 0
	v_mbcnt_hi_u32_b32 v2, s37, v2
	v_cmp_eq_u32_e32 vcc, 0, v2
	s_and_saveexec_b64 s[2:3], vcc
	s_cbranch_execz .LBB0_955
	s_bcnt1_i32_b64 s33, s[36:37]
	s_lshl_b32 s33, s33, 1
	v_readlane_b32 s36, v252, 62
	v_mov_b32_e32 v3, s33
	v_readlane_b32 s37, v252, 63
	s_nop 4
	global_atomic_add v3, v83, v3, s[36:37] sc0
